# six steady-state GEMM K-loop heads aligned to 64 bytes (.p2align 6 behind the unconditional branch, padding never executed)
# baseline (speedup 1.0000x reference)
.LBB0_187:
	s_ashr_i32 s15, s14, 31
	s_lshl_b64 s[16:17], s[14:15], 19
	s_add_u32 s16, s30, s16
	s_addc_u32 s17, s31, s17
	s_and_b64 s[18:19], s[0:1], exec
	s_cselect_b32 s3, s17, s25
	s_cselect_b32 s15, s16, s24
	s_ashr_i32 s13, s12, 31
	s_lshl_b64 s[18:19], s[12:13], 19
	s_add_u32 s18, s34, s18
	s_addc_u32 s19, s35, s19
	s_and_b64 s[26:27], s[0:1], exec
	s_cselect_b32 s13, s19, s23
	s_cselect_b32 s21, s18, s22
	s_add_u32 s48, s22, 0x100
	s_addc_u32 s49, s23, 0
	s_add_u32 s22, s24, 0x40080
	s_addc_u32 s23, s25, 0
	s_mov_b32 s50, -2
	s_waitcnt vmcnt(0)
	s_add_u32 s24, s22, 0xfffc0080
	s_addc_u32 s25, s23, -1
	s_add_i32 s51, 0, 0x10000
	s_cmp_eq_u32 s50, 12
	s_cselect_b32 s27, s3, s25
	s_cselect_b32 s26, s15, s24
	v_add_u32_e32 v142, s51, v144
	s_cselect_b32 s25, s13, s49
	s_cselect_b32 s24, s21, s48
	s_add_i32 s54, 0, 0x14000
	ds_read_b128 v[138:141], v142
	ds_read_b128 v[146:149], v142 offset:1024
	ds_read_b128 v[150:153], v142 offset:2048
	ds_read_b128 v[154:157], v142 offset:3072
	v_add_u32_e32 v142, s54, v144
	ds_read_b128 v[158:161], v142
	ds_read_b128 v[162:165], v142 offset:1024
	ds_read_b128 v[166:169], v142 offset:2048
	ds_read_b128 v[170:173], v142 offset:3072
	v_lshl_add_u64 v[142:143], s[22:23], 0, v[136:137]
	s_add_i32 m0, s37, 0xc000
	ds_read_b128 v[174:177], v145
	ds_read_b128 v[178:181], v145 offset:1024
	ds_read_b128 v[182:185], v145 offset:2048
	ds_read_b128 v[186:189], v145 offset:3072
	ds_read_b128 v[190:193], v145 offset:4096
	ds_read_b128 v[194:197], v145 offset:5120
	ds_read_b128 v[198:201], v145 offset:6144
	ds_read_b128 v[202:205], v145 offset:7168
	global_load_lds_dwordx4 v[142:143], off
	v_lshl_add_u64 v[142:143], s[22:23], 0, v[134:135]
	s_add_i32 m0, s37, 0xe000
	s_nop 0
	global_load_lds_dwordx4 v[142:143], off
	s_waitcnt vmcnt(8)
	s_waitcnt lgkmcnt(0)
	s_barrier
	v_mfma_f32_16x16x32_bf16 v[124:127], v[138:141], v[174:177], 0
	v_mfma_f32_16x16x32_bf16 v[120:123], v[150:153], v[174:177], 0
	v_mfma_f32_16x16x32_bf16 v[112:115], v[138:141], v[182:185], 0
	v_mfma_f32_16x16x32_bf16 v[104:107], v[150:153], v[182:185], 0
	v_mfma_f32_16x16x32_bf16 v[96:99], v[138:141], v[190:193], 0
	v_mfma_f32_16x16x32_bf16 v[88:91], v[150:153], v[190:193], 0
	v_mfma_f32_16x16x32_bf16 v[80:83], v[138:141], v[198:201], 0
	v_mfma_f32_16x16x32_bf16 v[72:75], v[150:153], v[198:201], 0
	v_mfma_f32_16x16x32_bf16 v[124:127], v[146:149], v[178:181], v[124:127]
	v_mfma_f32_16x16x32_bf16 v[120:123], v[154:157], v[178:181], v[120:123]
	v_mfma_f32_16x16x32_bf16 v[112:115], v[146:149], v[186:189], v[112:115]
	v_mfma_f32_16x16x32_bf16 v[104:107], v[154:157], v[186:189], v[104:107]
	v_mfma_f32_16x16x32_bf16 v[96:99], v[146:149], v[194:197], v[96:99]
	v_mfma_f32_16x16x32_bf16 v[88:91], v[154:157], v[194:197], v[88:91]
	v_mfma_f32_16x16x32_bf16 v[80:83], v[146:149], v[202:205], v[80:83]
	v_mfma_f32_16x16x32_bf16 v[72:75], v[154:157], v[202:205], v[72:75]
	v_mfma_f32_16x16x32_bf16 v[116:119], v[158:161], v[174:177], 0
	v_mfma_f32_16x16x32_bf16 v[108:111], v[166:169], v[174:177], 0
	v_mfma_f32_16x16x32_bf16 v[100:103], v[158:161], v[182:185], 0
	v_mfma_f32_16x16x32_bf16 v[92:95], v[166:169], v[182:185], 0
	v_mfma_f32_16x16x32_bf16 v[84:87], v[158:161], v[190:193], 0
	v_mfma_f32_16x16x32_bf16 v[76:79], v[166:169], v[190:193], 0
	v_mfma_f32_16x16x32_bf16 v[68:71], v[158:161], v[198:201], 0
	v_mfma_f32_16x16x32_bf16 v[64:67], v[166:169], v[198:201], 0
	v_mfma_f32_16x16x32_bf16 v[116:119], v[162:165], v[178:181], v[116:119]
	v_mfma_f32_16x16x32_bf16 v[108:111], v[170:173], v[178:181], v[108:111]
	v_mfma_f32_16x16x32_bf16 v[100:103], v[162:165], v[186:189], v[100:103]
	v_mfma_f32_16x16x32_bf16 v[92:95], v[170:173], v[186:189], v[92:95]
	v_mfma_f32_16x16x32_bf16 v[84:87], v[162:165], v[194:197], v[84:87]
	v_mfma_f32_16x16x32_bf16 v[76:79], v[170:173], v[194:197], v[76:79]
	v_mfma_f32_16x16x32_bf16 v[68:71], v[162:165], v[202:205], v[68:71]
	v_mfma_f32_16x16x32_bf16 v[64:67], v[170:173], v[202:205], v[64:67]
	s_barrier
	s_add_i32 s51, s51, s36
	v_lshl_add_u64 v[142:143], s[24:25], 0, v[232:233]
	s_mov_b32 m0, s51
	ds_read_b128 v[174:177], v145 offset:16384
	ds_read_b128 v[178:181], v145 offset:17408
	ds_read_b128 v[182:185], v145 offset:18432
	ds_read_b128 v[186:189], v145 offset:19456
	ds_read_b128 v[190:193], v145 offset:20480
	ds_read_b128 v[194:197], v145 offset:21504
	ds_read_b128 v[198:201], v145 offset:22528
	ds_read_b128 v[202:205], v145 offset:23552
	global_load_lds_dwordx4 v[142:143], off
	s_add_i32 m0, s51, 0x2000
	s_add_u32 s52, s24, 0x40000
	v_lshl_add_u64 v[206:207], s[24:25], 0, v[132:133]
	s_addc_u32 s53, s25, 0
	s_add_i32 s51, s54, s36
	global_load_lds_dwordx4 v[206:207], off
	v_lshl_add_u64 v[208:209], s[52:53], 0, v[232:233]
	s_mov_b32 m0, s51
	v_lshl_add_u64 v[210:211], s[26:27], 0, v[130:131]
	global_load_lds_dwordx4 v[208:209], off
	v_lshl_add_u64 v[208:209], s[52:53], 0, v[132:133]
	s_add_i32 m0, s51, 0x2000
	s_nop 0
	global_load_lds_dwordx4 v[208:209], off
	v_lshl_add_u64 v[208:209], s[26:27], 0, v[128:129]
	s_waitcnt vmcnt(6)
	s_waitcnt lgkmcnt(0)
	s_barrier
	v_mfma_f32_16x16x32_bf16 v[60:63], v[138:141], v[174:177], 0
	v_mfma_f32_16x16x32_bf16 v[56:59], v[150:153], v[174:177], 0
	v_mfma_f32_16x16x32_bf16 v[48:51], v[138:141], v[182:185], 0
	v_mfma_f32_16x16x32_bf16 v[40:43], v[150:153], v[182:185], 0
	v_mfma_f32_16x16x32_bf16 v[32:35], v[138:141], v[190:193], 0
	v_mfma_f32_16x16x32_bf16 v[24:27], v[150:153], v[190:193], 0
	v_mfma_f32_16x16x32_bf16 v[16:19], v[138:141], v[198:201], 0
	v_mfma_f32_16x16x32_bf16 v[8:11], v[150:153], v[198:201], 0
	v_mfma_f32_16x16x32_bf16 v[60:63], v[146:149], v[178:181], v[60:63]
	v_mfma_f32_16x16x32_bf16 v[56:59], v[154:157], v[178:181], v[56:59]
	v_mfma_f32_16x16x32_bf16 v[48:51], v[146:149], v[186:189], v[48:51]
	v_mfma_f32_16x16x32_bf16 v[40:43], v[154:157], v[186:189], v[40:43]
	v_mfma_f32_16x16x32_bf16 v[32:35], v[146:149], v[194:197], v[32:35]
	v_mfma_f32_16x16x32_bf16 v[24:27], v[154:157], v[194:197], v[24:27]
	v_mfma_f32_16x16x32_bf16 v[16:19], v[146:149], v[202:205], v[16:19]
	v_mfma_f32_16x16x32_bf16 v[8:11], v[154:157], v[202:205], v[8:11]
	v_mfma_f32_16x16x32_bf16 v[52:55], v[158:161], v[174:177], 0
	v_mfma_f32_16x16x32_bf16 v[44:47], v[166:169], v[174:177], 0
	v_mfma_f32_16x16x32_bf16 v[36:39], v[158:161], v[182:185], 0
	v_mfma_f32_16x16x32_bf16 v[28:31], v[166:169], v[182:185], 0
	v_mfma_f32_16x16x32_bf16 v[20:23], v[158:161], v[190:193], 0
	v_mfma_f32_16x16x32_bf16 v[12:15], v[166:169], v[190:193], 0
	v_mfma_f32_16x16x32_bf16 v[4:7], v[158:161], v[198:201], 0
	v_mfma_f32_16x16x32_bf16 v[0:3], v[166:169], v[198:201], 0
	v_mfma_f32_16x16x32_bf16 v[52:55], v[162:165], v[178:181], v[52:55]
	v_mfma_f32_16x16x32_bf16 v[44:47], v[170:173], v[178:181], v[44:47]
	v_mfma_f32_16x16x32_bf16 v[36:39], v[162:165], v[186:189], v[36:39]
	v_mfma_f32_16x16x32_bf16 v[28:31], v[170:173], v[186:189], v[28:31]
	v_mfma_f32_16x16x32_bf16 v[20:23], v[162:165], v[194:197], v[20:23]
	v_mfma_f32_16x16x32_bf16 v[12:15], v[170:173], v[194:197], v[12:15]
	v_mfma_f32_16x16x32_bf16 v[4:7], v[162:165], v[202:205], v[4:7]
	v_mfma_f32_16x16x32_bf16 v[0:3], v[170:173], v[202:205], v[0:3]
	s_barrier
	s_branch .Lzmid_1
	.p2align 6

.LBB0_911:
	s_ashr_i32 s15, s14, 31
	s_lshl_b64 s[16:17], s[14:15], 19
	s_add_u32 s16, s30, s16
	s_addc_u32 s17, s31, s17
	s_and_b64 s[18:19], s[2:3], exec
	s_cselect_b32 s5, s17, s25
	s_cselect_b32 s15, s16, s24
	s_ashr_i32 s13, s12, 31
	s_lshl_b64 s[18:19], s[12:13], 19
	s_add_u32 s18, s34, s18
	s_addc_u32 s19, s35, s19
	s_and_b64 s[26:27], s[2:3], exec
	s_cselect_b32 s13, s19, s23
	s_cselect_b32 s21, s18, s22
	s_add_u32 s48, s22, 0x100
	s_addc_u32 s49, s23, 0
	s_add_u32 s22, s24, 0x40080
	s_addc_u32 s23, s25, 0
	s_mov_b32 s50, -2
	s_add_u32 s24, s22, 0xfffc0080
	s_addc_u32 s25, s23, -1
	s_add_i32 s51, 0, 0x10000
	s_cmp_eq_u32 s50, 12
	s_cselect_b32 s27, s5, s25
	s_cselect_b32 s26, s15, s24
	v_add_u32_e32 v142, s51, v144
	s_cselect_b32 s25, s13, s49
	s_cselect_b32 s24, s21, s48
	s_add_i32 s54, 0, 0x14000
	ds_read_b128 v[138:141], v142
	ds_read_b128 v[146:149], v142 offset:1024
	ds_read_b128 v[150:153], v142 offset:2048
	ds_read_b128 v[154:157], v142 offset:3072
	v_add_u32_e32 v142, s54, v144
	ds_read_b128 v[158:161], v142
	ds_read_b128 v[162:165], v142 offset:1024
	ds_read_b128 v[166:169], v142 offset:2048
	ds_read_b128 v[170:173], v142 offset:3072
	v_lshl_add_u64 v[142:143], s[22:23], 0, v[136:137]
	s_add_i32 m0, s37, 0xc000
	ds_read_b128 v[174:177], v145
	ds_read_b128 v[178:181], v145 offset:1024
	ds_read_b128 v[182:185], v145 offset:2048
	ds_read_b128 v[186:189], v145 offset:3072
	ds_read_b128 v[190:193], v145 offset:4096
	ds_read_b128 v[194:197], v145 offset:5120
	ds_read_b128 v[198:201], v145 offset:6144
	ds_read_b128 v[202:205], v145 offset:7168
	global_load_lds_dwordx4 v[142:143], off
	v_lshl_add_u64 v[142:143], s[22:23], 0, v[134:135]
	s_add_i32 m0, s37, 0xe000
	s_nop 0
	global_load_lds_dwordx4 v[142:143], off
	s_waitcnt vmcnt(8)
	s_waitcnt lgkmcnt(0)
	s_barrier
	v_mfma_f32_16x16x32_bf16 v[124:127], v[138:141], v[174:177], 0
	v_mfma_f32_16x16x32_bf16 v[120:123], v[150:153], v[174:177], 0
	v_mfma_f32_16x16x32_bf16 v[108:111], v[138:141], v[182:185], 0
	v_mfma_f32_16x16x32_bf16 v[104:107], v[150:153], v[182:185], 0
	v_mfma_f32_16x16x32_bf16 v[92:95], v[138:141], v[190:193], 0
	v_mfma_f32_16x16x32_bf16 v[88:91], v[150:153], v[190:193], 0
	v_mfma_f32_16x16x32_bf16 v[76:79], v[138:141], v[198:201], 0
	v_mfma_f32_16x16x32_bf16 v[72:75], v[150:153], v[198:201], 0
	v_mfma_f32_16x16x32_bf16 v[124:127], v[146:149], v[178:181], v[124:127]
	v_mfma_f32_16x16x32_bf16 v[120:123], v[154:157], v[178:181], v[120:123]
	v_mfma_f32_16x16x32_bf16 v[108:111], v[146:149], v[186:189], v[108:111]
	v_mfma_f32_16x16x32_bf16 v[104:107], v[154:157], v[186:189], v[104:107]
	v_mfma_f32_16x16x32_bf16 v[92:95], v[146:149], v[194:197], v[92:95]
	v_mfma_f32_16x16x32_bf16 v[88:91], v[154:157], v[194:197], v[88:91]
	v_mfma_f32_16x16x32_bf16 v[76:79], v[146:149], v[202:205], v[76:79]
	v_mfma_f32_16x16x32_bf16 v[72:75], v[154:157], v[202:205], v[72:75]
	v_mfma_f32_16x16x32_bf16 v[116:119], v[158:161], v[174:177], 0
	v_mfma_f32_16x16x32_bf16 v[112:115], v[166:169], v[174:177], 0
	v_mfma_f32_16x16x32_bf16 v[100:103], v[158:161], v[182:185], 0
	v_mfma_f32_16x16x32_bf16 v[96:99], v[166:169], v[182:185], 0
	v_mfma_f32_16x16x32_bf16 v[84:87], v[158:161], v[190:193], 0
	v_mfma_f32_16x16x32_bf16 v[80:83], v[166:169], v[190:193], 0
	v_mfma_f32_16x16x32_bf16 v[68:71], v[158:161], v[198:201], 0
	v_mfma_f32_16x16x32_bf16 v[64:67], v[166:169], v[198:201], 0
	v_mfma_f32_16x16x32_bf16 v[116:119], v[162:165], v[178:181], v[116:119]
	v_mfma_f32_16x16x32_bf16 v[112:115], v[170:173], v[178:181], v[112:115]
	v_mfma_f32_16x16x32_bf16 v[100:103], v[162:165], v[186:189], v[100:103]
	v_mfma_f32_16x16x32_bf16 v[96:99], v[170:173], v[186:189], v[96:99]
	v_mfma_f32_16x16x32_bf16 v[84:87], v[162:165], v[194:197], v[84:87]
	v_mfma_f32_16x16x32_bf16 v[80:83], v[170:173], v[194:197], v[80:83]
	v_mfma_f32_16x16x32_bf16 v[68:71], v[162:165], v[202:205], v[68:71]
	v_mfma_f32_16x16x32_bf16 v[64:67], v[170:173], v[202:205], v[64:67]
	s_barrier
	s_add_i32 s51, s51, s36
	v_lshl_add_u64 v[142:143], s[24:25], 0, v[232:233]
	s_mov_b32 m0, s51
	ds_read_b128 v[174:177], v145 offset:16384
	ds_read_b128 v[178:181], v145 offset:17408
	ds_read_b128 v[182:185], v145 offset:18432
	ds_read_b128 v[186:189], v145 offset:19456
	ds_read_b128 v[190:193], v145 offset:20480
	ds_read_b128 v[194:197], v145 offset:21504
	ds_read_b128 v[198:201], v145 offset:22528
	ds_read_b128 v[202:205], v145 offset:23552
	global_load_lds_dwordx4 v[142:143], off
	s_add_i32 m0, s51, 0x2000
	s_add_u32 s52, s24, 0x40000
	v_lshl_add_u64 v[206:207], s[24:25], 0, v[132:133]
	s_addc_u32 s53, s25, 0
	s_add_i32 s51, s54, s36
	global_load_lds_dwordx4 v[206:207], off
	v_lshl_add_u64 v[208:209], s[52:53], 0, v[232:233]
	s_mov_b32 m0, s51
	v_lshl_add_u64 v[210:211], s[26:27], 0, v[130:131]
	global_load_lds_dwordx4 v[208:209], off
	v_lshl_add_u64 v[208:209], s[52:53], 0, v[132:133]
	s_add_i32 m0, s51, 0x2000
	s_nop 0
	global_load_lds_dwordx4 v[208:209], off
	v_lshl_add_u64 v[208:209], s[26:27], 0, v[128:129]
	s_waitcnt vmcnt(6)
	s_waitcnt lgkmcnt(0)
	s_barrier
	v_mfma_f32_16x16x32_bf16 v[60:63], v[138:141], v[174:177], 0
	v_mfma_f32_16x16x32_bf16 v[56:59], v[150:153], v[174:177], 0
	v_mfma_f32_16x16x32_bf16 v[44:47], v[138:141], v[182:185], 0
	v_mfma_f32_16x16x32_bf16 v[40:43], v[150:153], v[182:185], 0
	v_mfma_f32_16x16x32_bf16 v[28:31], v[138:141], v[190:193], 0
	v_mfma_f32_16x16x32_bf16 v[24:27], v[150:153], v[190:193], 0
	v_mfma_f32_16x16x32_bf16 v[12:15], v[138:141], v[198:201], 0
	v_mfma_f32_16x16x32_bf16 v[8:11], v[150:153], v[198:201], 0
	v_mfma_f32_16x16x32_bf16 v[60:63], v[146:149], v[178:181], v[60:63]
	v_mfma_f32_16x16x32_bf16 v[56:59], v[154:157], v[178:181], v[56:59]
	v_mfma_f32_16x16x32_bf16 v[44:47], v[146:149], v[186:189], v[44:47]
	v_mfma_f32_16x16x32_bf16 v[40:43], v[154:157], v[186:189], v[40:43]
	v_mfma_f32_16x16x32_bf16 v[28:31], v[146:149], v[194:197], v[28:31]
	v_mfma_f32_16x16x32_bf16 v[24:27], v[154:157], v[194:197], v[24:27]
	v_mfma_f32_16x16x32_bf16 v[12:15], v[146:149], v[202:205], v[12:15]
	v_mfma_f32_16x16x32_bf16 v[8:11], v[154:157], v[202:205], v[8:11]
	v_mfma_f32_16x16x32_bf16 v[52:55], v[158:161], v[174:177], 0
	v_mfma_f32_16x16x32_bf16 v[48:51], v[166:169], v[174:177], 0
	v_mfma_f32_16x16x32_bf16 v[36:39], v[158:161], v[182:185], 0
	v_mfma_f32_16x16x32_bf16 v[32:35], v[166:169], v[182:185], 0
	v_mfma_f32_16x16x32_bf16 v[20:23], v[158:161], v[190:193], 0
	v_mfma_f32_16x16x32_bf16 v[16:19], v[166:169], v[190:193], 0
	v_mfma_f32_16x16x32_bf16 v[4:7], v[158:161], v[198:201], 0
	v_mfma_f32_16x16x32_bf16 v[0:3], v[166:169], v[198:201], 0
	v_mfma_f32_16x16x32_bf16 v[52:55], v[162:165], v[178:181], v[52:55]
	v_mfma_f32_16x16x32_bf16 v[48:51], v[170:173], v[178:181], v[48:51]
	v_mfma_f32_16x16x32_bf16 v[36:39], v[162:165], v[186:189], v[36:39]
	v_mfma_f32_16x16x32_bf16 v[32:35], v[170:173], v[186:189], v[32:35]
	v_mfma_f32_16x16x32_bf16 v[20:23], v[162:165], v[194:197], v[20:23]
	v_mfma_f32_16x16x32_bf16 v[16:19], v[170:173], v[194:197], v[16:19]
	v_mfma_f32_16x16x32_bf16 v[4:7], v[162:165], v[202:205], v[4:7]
	v_mfma_f32_16x16x32_bf16 v[0:3], v[170:173], v[202:205], v[0:3]
	s_barrier
	s_branch .Lzmid_2
	.p2align 6

.LBB0_1163:
	s_ashr_i32 s23, s22, 31
	s_lshl_b64 s[24:25], s[22:23], 19
	s_add_u32 s24, s42, s24
	s_addc_u32 s25, s43, s25
	s_and_b64 s[26:27], s[4:5], exec
	s_cselect_b32 s23, s25, s35
	s_cselect_b32 s56, s24, s34
	s_ashr_i32 s21, s20, 31
	s_lshl_b64 s[26:27], s[20:21], 19
	s_add_u32 s26, s44, s26
	s_addc_u32 s27, s45, s27
	s_and_b64 s[36:37], s[4:5], exec
	s_cselect_b32 s21, s27, s31
	s_cselect_b32 s57, s26, s30
	s_add_u32 s58, s30, 0x100
	s_addc_u32 s59, s31, 0
	s_add_u32 s30, s34, 0x40080
	s_addc_u32 s31, s35, 0
	s_mov_b32 s60, -2
	s_waitcnt vmcnt(0)
	s_add_u32 s34, s30, 0xfffc0080
	s_addc_u32 s35, s31, -1
	s_add_i32 s61, 0, 0x10000
	s_cmp_eq_u32 s60, 12
	s_cselect_b32 s37, s23, s35
	s_cselect_b32 s36, s56, s34
	s_cselect_b32 s35, s21, s59
	s_cselect_b32 s34, s57, s58
	s_add_i32 s64, 0, 0x14000
	v_add_u32_e32 v140, s61, v174
	v_add_u32_e32 v166, s64, v174
	ds_read_b128 v[128:131], v140
	ds_read_b128 v[132:135], v140 offset:1024
	ds_read_b128 v[136:139], v140 offset:2048
	ds_read_b128 v[140:143], v140 offset:3072
	ds_read_b128 v[154:157], v166
	ds_read_b128 v[158:161], v166 offset:1024
	ds_read_b128 v[162:165], v166 offset:2048
	ds_read_b128 v[166:169], v166 offset:3072
	v_lshl_add_u64 v[204:205], s[30:31], 0, v[152:153]
	s_add_i32 m0, s29, 0xc000
	ds_read_b128 v[170:173], v175
	ds_read_b128 v[176:179], v175 offset:1024
	ds_read_b128 v[180:183], v175 offset:2048
	ds_read_b128 v[184:187], v175 offset:3072
	ds_read_b128 v[188:191], v175 offset:4096
	ds_read_b128 v[192:195], v175 offset:5120
	ds_read_b128 v[196:199], v175 offset:6144
	ds_read_b128 v[200:203], v175 offset:7168
	global_load_lds_dwordx4 v[204:205], off
	v_lshl_add_u64 v[204:205], s[30:31], 0, v[150:151]
	s_add_i32 m0, s29, 0xe000
	s_nop 0
	global_load_lds_dwordx4 v[204:205], off
	s_waitcnt vmcnt(8)
	s_waitcnt lgkmcnt(0)
	s_barrier
	v_mfma_f32_16x16x32_bf16 v[124:127], v[128:131], v[170:173], 0
	v_mfma_f32_16x16x32_bf16 v[120:123], v[136:139], v[170:173], 0
	v_mfma_f32_16x16x32_bf16 v[108:111], v[128:131], v[180:183], 0
	v_mfma_f32_16x16x32_bf16 v[104:107], v[136:139], v[180:183], 0
	v_mfma_f32_16x16x32_bf16 v[92:95], v[128:131], v[188:191], 0
	v_mfma_f32_16x16x32_bf16 v[88:91], v[136:139], v[188:191], 0
	v_mfma_f32_16x16x32_bf16 v[80:83], v[128:131], v[196:199], 0
	v_mfma_f32_16x16x32_bf16 v[72:75], v[136:139], v[196:199], 0
	v_mfma_f32_16x16x32_bf16 v[124:127], v[132:135], v[176:179], v[124:127]
	v_mfma_f32_16x16x32_bf16 v[120:123], v[140:143], v[176:179], v[120:123]
	v_mfma_f32_16x16x32_bf16 v[108:111], v[132:135], v[184:187], v[108:111]
	v_mfma_f32_16x16x32_bf16 v[104:107], v[140:143], v[184:187], v[104:107]
	v_mfma_f32_16x16x32_bf16 v[92:95], v[132:135], v[192:195], v[92:95]
	v_mfma_f32_16x16x32_bf16 v[88:91], v[140:143], v[192:195], v[88:91]
	v_mfma_f32_16x16x32_bf16 v[80:83], v[132:135], v[200:203], v[80:83]
	v_mfma_f32_16x16x32_bf16 v[72:75], v[140:143], v[200:203], v[72:75]
	v_mfma_f32_16x16x32_bf16 v[116:119], v[154:157], v[170:173], 0
	v_mfma_f32_16x16x32_bf16 v[112:115], v[162:165], v[170:173], 0
	v_mfma_f32_16x16x32_bf16 v[100:103], v[154:157], v[180:183], 0
	v_mfma_f32_16x16x32_bf16 v[96:99], v[162:165], v[180:183], 0
	v_mfma_f32_16x16x32_bf16 v[84:87], v[154:157], v[188:191], 0
	v_mfma_f32_16x16x32_bf16 v[76:79], v[162:165], v[188:191], 0
	v_mfma_f32_16x16x32_bf16 v[68:71], v[154:157], v[196:199], 0
	v_mfma_f32_16x16x32_bf16 v[64:67], v[162:165], v[196:199], 0
	v_mfma_f32_16x16x32_bf16 v[116:119], v[158:161], v[176:179], v[116:119]
	v_mfma_f32_16x16x32_bf16 v[112:115], v[166:169], v[176:179], v[112:115]
	v_mfma_f32_16x16x32_bf16 v[100:103], v[158:161], v[184:187], v[100:103]
	v_mfma_f32_16x16x32_bf16 v[96:99], v[166:169], v[184:187], v[96:99]
	v_mfma_f32_16x16x32_bf16 v[84:87], v[158:161], v[192:195], v[84:87]
	v_mfma_f32_16x16x32_bf16 v[76:79], v[166:169], v[192:195], v[76:79]
	v_mfma_f32_16x16x32_bf16 v[68:71], v[158:161], v[200:203], v[68:71]
	v_mfma_f32_16x16x32_bf16 v[64:67], v[166:169], v[200:203], v[64:67]
	s_barrier
	s_add_i32 s61, s61, s41
	v_lshl_add_u64 v[204:205], s[34:35], 0, v[232:233]
	s_mov_b32 m0, s61
	ds_read_b128 v[170:173], v175 offset:16384
	ds_read_b128 v[176:179], v175 offset:17408
	ds_read_b128 v[180:183], v175 offset:18432
	ds_read_b128 v[184:187], v175 offset:19456
	ds_read_b128 v[188:191], v175 offset:20480
	ds_read_b128 v[192:195], v175 offset:21504
	ds_read_b128 v[196:199], v175 offset:22528
	ds_read_b128 v[200:203], v175 offset:23552
	global_load_lds_dwordx4 v[204:205], off
	s_add_i32 m0, s61, 0x2000
	s_add_u32 s62, s34, 0x40000
	v_lshl_add_u64 v[206:207], s[34:35], 0, v[148:149]
	s_addc_u32 s63, s35, 0
	s_add_i32 s61, s64, s41
	global_load_lds_dwordx4 v[206:207], off
	v_lshl_add_u64 v[208:209], s[62:63], 0, v[232:233]
	s_mov_b32 m0, s61
	v_lshl_add_u64 v[210:211], s[36:37], 0, v[146:147]
	global_load_lds_dwordx4 v[208:209], off
	v_lshl_add_u64 v[208:209], s[62:63], 0, v[148:149]
	s_add_i32 m0, s61, 0x2000
	s_nop 0
	global_load_lds_dwordx4 v[208:209], off
	v_lshl_add_u64 v[208:209], s[36:37], 0, v[144:145]
	s_waitcnt vmcnt(6)
	s_waitcnt lgkmcnt(0)
	s_barrier
	v_mfma_f32_16x16x32_bf16 v[60:63], v[128:131], v[170:173], 0
	v_mfma_f32_16x16x32_bf16 v[56:59], v[136:139], v[170:173], 0
	v_mfma_f32_16x16x32_bf16 v[48:51], v[128:131], v[180:183], 0
	v_mfma_f32_16x16x32_bf16 v[40:43], v[136:139], v[180:183], 0
	v_mfma_f32_16x16x32_bf16 v[28:31], v[128:131], v[188:191], 0
	v_mfma_f32_16x16x32_bf16 v[24:27], v[136:139], v[188:191], 0
	v_mfma_f32_16x16x32_bf16 v[16:19], v[128:131], v[196:199], 0
	v_mfma_f32_16x16x32_bf16 v[8:11], v[136:139], v[196:199], 0
	v_mfma_f32_16x16x32_bf16 v[60:63], v[132:135], v[176:179], v[60:63]
	v_mfma_f32_16x16x32_bf16 v[56:59], v[140:143], v[176:179], v[56:59]
	v_mfma_f32_16x16x32_bf16 v[48:51], v[132:135], v[184:187], v[48:51]
	v_mfma_f32_16x16x32_bf16 v[40:43], v[140:143], v[184:187], v[40:43]
	v_mfma_f32_16x16x32_bf16 v[28:31], v[132:135], v[192:195], v[28:31]
	v_mfma_f32_16x16x32_bf16 v[24:27], v[140:143], v[192:195], v[24:27]
	v_mfma_f32_16x16x32_bf16 v[16:19], v[132:135], v[200:203], v[16:19]
	v_mfma_f32_16x16x32_bf16 v[8:11], v[140:143], v[200:203], v[8:11]
	v_mfma_f32_16x16x32_bf16 v[52:55], v[154:157], v[170:173], 0
	v_mfma_f32_16x16x32_bf16 v[44:47], v[162:165], v[170:173], 0
	v_mfma_f32_16x16x32_bf16 v[36:39], v[154:157], v[180:183], 0
	v_mfma_f32_16x16x32_bf16 v[32:35], v[162:165], v[180:183], 0
	v_mfma_f32_16x16x32_bf16 v[20:23], v[154:157], v[188:191], 0
	v_mfma_f32_16x16x32_bf16 v[12:15], v[162:165], v[188:191], 0
	v_mfma_f32_16x16x32_bf16 v[4:7], v[154:157], v[196:199], 0
	v_mfma_f32_16x16x32_bf16 v[0:3], v[162:165], v[196:199], 0
	v_mfma_f32_16x16x32_bf16 v[52:55], v[158:161], v[176:179], v[52:55]
	v_mfma_f32_16x16x32_bf16 v[44:47], v[166:169], v[176:179], v[44:47]
	v_mfma_f32_16x16x32_bf16 v[36:39], v[158:161], v[184:187], v[36:39]
	v_mfma_f32_16x16x32_bf16 v[32:35], v[166:169], v[184:187], v[32:35]
	v_mfma_f32_16x16x32_bf16 v[20:23], v[158:161], v[192:195], v[20:23]
	v_mfma_f32_16x16x32_bf16 v[12:15], v[166:169], v[192:195], v[12:15]
	v_mfma_f32_16x16x32_bf16 v[4:7], v[158:161], v[200:203], v[4:7]
	v_mfma_f32_16x16x32_bf16 v[0:3], v[166:169], v[200:203], v[0:3]
	s_barrier
	s_branch .Lzmid_3
	.p2align 6

.LBB0_1306:
	s_ashr_i32 s17, s16, 31
	s_lshl_b64 s[18:19], s[16:17], 19
	s_add_u32 s18, s34, s18
	s_addc_u32 s19, s35, s19
	s_and_b64 s[20:21], s[4:5], exec
	s_cselect_b32 s7, s19, s27
	s_cselect_b32 s17, s18, s26
	s_ashr_i32 s15, s14, 31
	s_lshl_b64 s[20:21], s[14:15], 19
	s_add_u32 s20, s36, s20
	s_addc_u32 s21, s37, s21
	s_and_b64 s[28:29], s[4:5], exec
	s_cselect_b32 s15, s21, s25
	s_cselect_b32 s23, s20, s24
	s_add_u32 s50, s24, 0x100
	s_addc_u32 s51, s25, 0
	s_add_u32 s24, s26, 0x40080
	s_addc_u32 s25, s27, 0
	s_mov_b32 s52, -2
	s_add_u32 s26, s24, 0xfffc0080
	s_addc_u32 s27, s25, -1
	s_add_i32 s53, 0, 0x10000
	s_cmp_eq_u32 s52, 12
	s_cselect_b32 s29, s7, s27
	s_cselect_b32 s28, s17, s26
	v_add_u32_e32 v142, s53, v144
	s_cselect_b32 s27, s15, s51
	s_cselect_b32 s26, s23, s50
	s_add_i32 s56, 0, 0x14000
	ds_read_b128 v[138:141], v142
	ds_read_b128 v[146:149], v142 offset:1024
	ds_read_b128 v[150:153], v142 offset:2048
	ds_read_b128 v[154:157], v142 offset:3072
	v_add_u32_e32 v142, s56, v144
	ds_read_b128 v[158:161], v142
	ds_read_b128 v[162:165], v142 offset:1024
	ds_read_b128 v[166:169], v142 offset:2048
	ds_read_b128 v[170:173], v142 offset:3072
	v_lshl_add_u64 v[142:143], s[24:25], 0, v[136:137]
	s_add_i32 m0, s39, 0xc000
	ds_read_b128 v[174:177], v145
	ds_read_b128 v[178:181], v145 offset:1024
	ds_read_b128 v[182:185], v145 offset:2048
	ds_read_b128 v[186:189], v145 offset:3072
	ds_read_b128 v[190:193], v145 offset:4096
	ds_read_b128 v[194:197], v145 offset:5120
	ds_read_b128 v[198:201], v145 offset:6144
	ds_read_b128 v[202:205], v145 offset:7168
	global_load_lds_dwordx4 v[142:143], off
	v_lshl_add_u64 v[142:143], s[24:25], 0, v[134:135]
	s_add_i32 m0, s39, 0xe000
	s_nop 0
	global_load_lds_dwordx4 v[142:143], off
	s_waitcnt vmcnt(8)
	s_waitcnt lgkmcnt(0)
	s_barrier
	v_mfma_f32_16x16x32_bf16 v[124:127], v[138:141], v[174:177], 0
	v_mfma_f32_16x16x32_bf16 v[120:123], v[150:153], v[174:177], 0
	v_mfma_f32_16x16x32_bf16 v[108:111], v[138:141], v[182:185], 0
	v_mfma_f32_16x16x32_bf16 v[104:107], v[150:153], v[182:185], 0
	v_mfma_f32_16x16x32_bf16 v[92:95], v[138:141], v[190:193], 0
	v_mfma_f32_16x16x32_bf16 v[88:91], v[150:153], v[190:193], 0
	v_mfma_f32_16x16x32_bf16 v[76:79], v[138:141], v[198:201], 0
	v_mfma_f32_16x16x32_bf16 v[72:75], v[150:153], v[198:201], 0
	v_mfma_f32_16x16x32_bf16 v[124:127], v[146:149], v[178:181], v[124:127]
	v_mfma_f32_16x16x32_bf16 v[120:123], v[154:157], v[178:181], v[120:123]
	v_mfma_f32_16x16x32_bf16 v[108:111], v[146:149], v[186:189], v[108:111]
	v_mfma_f32_16x16x32_bf16 v[104:107], v[154:157], v[186:189], v[104:107]
	v_mfma_f32_16x16x32_bf16 v[92:95], v[146:149], v[194:197], v[92:95]
	v_mfma_f32_16x16x32_bf16 v[88:91], v[154:157], v[194:197], v[88:91]
	v_mfma_f32_16x16x32_bf16 v[76:79], v[146:149], v[202:205], v[76:79]
	v_mfma_f32_16x16x32_bf16 v[72:75], v[154:157], v[202:205], v[72:75]
	v_mfma_f32_16x16x32_bf16 v[116:119], v[158:161], v[174:177], 0
	v_mfma_f32_16x16x32_bf16 v[112:115], v[166:169], v[174:177], 0
	v_mfma_f32_16x16x32_bf16 v[100:103], v[158:161], v[182:185], 0
	v_mfma_f32_16x16x32_bf16 v[96:99], v[166:169], v[182:185], 0
	v_mfma_f32_16x16x32_bf16 v[84:87], v[158:161], v[190:193], 0
	v_mfma_f32_16x16x32_bf16 v[80:83], v[166:169], v[190:193], 0
	v_mfma_f32_16x16x32_bf16 v[68:71], v[158:161], v[198:201], 0
	v_mfma_f32_16x16x32_bf16 v[64:67], v[166:169], v[198:201], 0
	v_mfma_f32_16x16x32_bf16 v[116:119], v[162:165], v[178:181], v[116:119]
	v_mfma_f32_16x16x32_bf16 v[112:115], v[170:173], v[178:181], v[112:115]
	v_mfma_f32_16x16x32_bf16 v[100:103], v[162:165], v[186:189], v[100:103]
	v_mfma_f32_16x16x32_bf16 v[96:99], v[170:173], v[186:189], v[96:99]
	v_mfma_f32_16x16x32_bf16 v[84:87], v[162:165], v[194:197], v[84:87]
	v_mfma_f32_16x16x32_bf16 v[80:83], v[170:173], v[194:197], v[80:83]
	v_mfma_f32_16x16x32_bf16 v[68:71], v[162:165], v[202:205], v[68:71]
	v_mfma_f32_16x16x32_bf16 v[64:67], v[170:173], v[202:205], v[64:67]
	s_barrier
	s_add_i32 s53, s53, s38
	v_lshl_add_u64 v[142:143], s[26:27], 0, v[232:233]
	s_mov_b32 m0, s53
	ds_read_b128 v[174:177], v145 offset:16384
	ds_read_b128 v[178:181], v145 offset:17408
	ds_read_b128 v[182:185], v145 offset:18432
	ds_read_b128 v[186:189], v145 offset:19456
	ds_read_b128 v[190:193], v145 offset:20480
	ds_read_b128 v[194:197], v145 offset:21504
	ds_read_b128 v[198:201], v145 offset:22528
	ds_read_b128 v[202:205], v145 offset:23552
	global_load_lds_dwordx4 v[142:143], off
	s_add_i32 m0, s53, 0x2000
	s_add_u32 s54, s26, 0x40000
	v_lshl_add_u64 v[206:207], s[26:27], 0, v[132:133]
	s_addc_u32 s55, s27, 0
	s_add_i32 s53, s56, s38
	global_load_lds_dwordx4 v[206:207], off
	v_lshl_add_u64 v[208:209], s[54:55], 0, v[232:233]
	s_mov_b32 m0, s53
	v_lshl_add_u64 v[210:211], s[28:29], 0, v[130:131]
	global_load_lds_dwordx4 v[208:209], off
	v_lshl_add_u64 v[208:209], s[54:55], 0, v[132:133]
	s_add_i32 m0, s53, 0x2000
	s_nop 0
	global_load_lds_dwordx4 v[208:209], off
	v_lshl_add_u64 v[208:209], s[28:29], 0, v[128:129]
	s_waitcnt vmcnt(6)
	s_waitcnt lgkmcnt(0)
	s_barrier
	v_mfma_f32_16x16x32_bf16 v[60:63], v[138:141], v[174:177], 0
	v_mfma_f32_16x16x32_bf16 v[56:59], v[150:153], v[174:177], 0
	v_mfma_f32_16x16x32_bf16 v[44:47], v[138:141], v[182:185], 0
	v_mfma_f32_16x16x32_bf16 v[40:43], v[150:153], v[182:185], 0
	v_mfma_f32_16x16x32_bf16 v[28:31], v[138:141], v[190:193], 0
	v_mfma_f32_16x16x32_bf16 v[24:27], v[150:153], v[190:193], 0
	v_mfma_f32_16x16x32_bf16 v[12:15], v[138:141], v[198:201], 0
	v_mfma_f32_16x16x32_bf16 v[8:11], v[150:153], v[198:201], 0
	v_mfma_f32_16x16x32_bf16 v[60:63], v[146:149], v[178:181], v[60:63]
	v_mfma_f32_16x16x32_bf16 v[56:59], v[154:157], v[178:181], v[56:59]
	v_mfma_f32_16x16x32_bf16 v[44:47], v[146:149], v[186:189], v[44:47]
	v_mfma_f32_16x16x32_bf16 v[40:43], v[154:157], v[186:189], v[40:43]
	v_mfma_f32_16x16x32_bf16 v[28:31], v[146:149], v[194:197], v[28:31]
	v_mfma_f32_16x16x32_bf16 v[24:27], v[154:157], v[194:197], v[24:27]
	v_mfma_f32_16x16x32_bf16 v[12:15], v[146:149], v[202:205], v[12:15]
	v_mfma_f32_16x16x32_bf16 v[8:11], v[154:157], v[202:205], v[8:11]
	v_mfma_f32_16x16x32_bf16 v[52:55], v[158:161], v[174:177], 0
	v_mfma_f32_16x16x32_bf16 v[48:51], v[166:169], v[174:177], 0
	v_mfma_f32_16x16x32_bf16 v[36:39], v[158:161], v[182:185], 0
	v_mfma_f32_16x16x32_bf16 v[32:35], v[166:169], v[182:185], 0
	v_mfma_f32_16x16x32_bf16 v[20:23], v[158:161], v[190:193], 0
	v_mfma_f32_16x16x32_bf16 v[16:19], v[166:169], v[190:193], 0
	v_mfma_f32_16x16x32_bf16 v[4:7], v[158:161], v[198:201], 0
	v_mfma_f32_16x16x32_bf16 v[0:3], v[166:169], v[198:201], 0
	v_mfma_f32_16x16x32_bf16 v[52:55], v[162:165], v[178:181], v[52:55]
	v_mfma_f32_16x16x32_bf16 v[48:51], v[170:173], v[178:181], v[48:51]
	v_mfma_f32_16x16x32_bf16 v[36:39], v[162:165], v[186:189], v[36:39]
	v_mfma_f32_16x16x32_bf16 v[32:35], v[170:173], v[186:189], v[32:35]
	v_mfma_f32_16x16x32_bf16 v[20:23], v[162:165], v[194:197], v[20:23]
	v_mfma_f32_16x16x32_bf16 v[16:19], v[170:173], v[194:197], v[16:19]
	v_mfma_f32_16x16x32_bf16 v[4:7], v[162:165], v[202:205], v[4:7]
	v_mfma_f32_16x16x32_bf16 v[0:3], v[170:173], v[202:205], v[0:3]
	s_barrier
	s_branch .Lzmid_4
	.p2align 6

.LBB0_1491:
	s_ashr_i32 s23, s22, 31
	s_lshl_b64 s[24:25], s[22:23], 21
	s_add_u32 s24, s70, s24
	s_addc_u32 s25, s71, s25
	s_and_b64 s[26:27], s[4:5], exec
	s_cselect_b32 s23, s25, s35
	s_cselect_b32 s56, s24, s34
	s_ashr_i32 s21, s20, 31
	s_lshl_b64 s[26:27], s[20:21], 21
	s_add_u32 s26, s72, s26
	s_addc_u32 s27, s76, s27
	s_and_b64 s[36:37], s[4:5], exec
	s_cselect_b32 s21, s27, s31
	s_cselect_b32 s57, s26, s30
	s_add_u32 s58, s30, 0x100
	s_addc_u32 s59, s31, 0
	s_add_u32 s30, s34, 0x100080
	s_addc_u32 s31, s35, 0
	s_mov_b32 s60, -2
	s_waitcnt vmcnt(0)
	s_add_u32 s34, s30, 0xfff00080
	s_addc_u32 s35, s31, -1
	s_add_i32 s61, 0, 0x10000
	s_cmp_eq_u32 s60, 60
	s_cselect_b32 s37, s23, s35
	s_cselect_b32 s36, s56, s34
	s_cselect_b32 s35, s21, s59
	s_cselect_b32 s34, s57, s58
	s_add_i32 s64, 0, 0x14000
	v_add_u32_e32 v100, s61, v220
	v_add_u32_e32 v156, s64, v220
	ds_read_b128 v[88:91], v100
	ds_read_b128 v[92:95], v100 offset:1024
	ds_read_b128 v[96:99], v100 offset:2048
	ds_read_b128 v[100:103], v100 offset:3072
	ds_read_b128 v[144:147], v156
	ds_read_b128 v[148:151], v156 offset:1024
	ds_read_b128 v[152:155], v156 offset:2048
	ds_read_b128 v[156:159], v156 offset:3072
	v_lshl_add_u64 v[202:203], s[30:31], 0, v[188:189]
	s_add_i32 m0, s78, 0xc000
	ds_read_b128 v[160:163], v221
	ds_read_b128 v[164:167], v221 offset:1024
	ds_read_b128 v[168:171], v221 offset:2048
	ds_read_b128 v[172:175], v221 offset:3072
	ds_read_b128 v[176:179], v221 offset:4096
	ds_read_b128 v[190:193], v221 offset:5120
	ds_read_b128 v[194:197], v221 offset:6144
	ds_read_b128 v[198:201], v221 offset:7168
	global_load_lds_dwordx4 v[202:203], off
	v_lshl_add_u64 v[202:203], s[30:31], 0, v[186:187]
	s_add_i32 m0, s78, 0xe000
	s_nop 0
	global_load_lds_dwordx4 v[202:203], off
	s_waitcnt vmcnt(8)
	s_waitcnt lgkmcnt(0)
	s_barrier
	v_mfma_f32_16x16x32_bf16 v[140:143], v[88:91], v[160:163], 0
	v_mfma_f32_16x16x32_bf16 v[136:139], v[96:99], v[160:163], 0
	v_mfma_f32_16x16x32_bf16 v[124:127], v[88:91], v[168:171], 0
	v_mfma_f32_16x16x32_bf16 v[120:123], v[96:99], v[168:171], 0
	v_mfma_f32_16x16x32_bf16 v[108:111], v[88:91], v[176:179], 0
	v_mfma_f32_16x16x32_bf16 v[104:107], v[96:99], v[176:179], 0
	v_mfma_f32_16x16x32_bf16 v[76:79], v[88:91], v[194:197], 0
	v_mfma_f32_16x16x32_bf16 v[72:75], v[96:99], v[194:197], 0
	v_mfma_f32_16x16x32_bf16 v[140:143], v[92:95], v[164:167], v[140:143]
	v_mfma_f32_16x16x32_bf16 v[136:139], v[100:103], v[164:167], v[136:139]
	v_mfma_f32_16x16x32_bf16 v[124:127], v[92:95], v[172:175], v[124:127]
	v_mfma_f32_16x16x32_bf16 v[120:123], v[100:103], v[172:175], v[120:123]
	v_mfma_f32_16x16x32_bf16 v[108:111], v[92:95], v[190:193], v[108:111]
	v_mfma_f32_16x16x32_bf16 v[104:107], v[100:103], v[190:193], v[104:107]
	v_mfma_f32_16x16x32_bf16 v[76:79], v[92:95], v[198:201], v[76:79]
	v_mfma_f32_16x16x32_bf16 v[72:75], v[100:103], v[198:201], v[72:75]
	v_mfma_f32_16x16x32_bf16 v[132:135], v[144:147], v[160:163], 0
	v_mfma_f32_16x16x32_bf16 v[128:131], v[152:155], v[160:163], 0
	v_mfma_f32_16x16x32_bf16 v[116:119], v[144:147], v[168:171], 0
	v_mfma_f32_16x16x32_bf16 v[112:115], v[152:155], v[168:171], 0
	v_mfma_f32_16x16x32_bf16 v[84:87], v[144:147], v[176:179], 0
	v_mfma_f32_16x16x32_bf16 v[80:83], v[152:155], v[176:179], 0
	v_mfma_f32_16x16x32_bf16 v[68:71], v[144:147], v[194:197], 0
	v_mfma_f32_16x16x32_bf16 v[64:67], v[152:155], v[194:197], 0
	v_mfma_f32_16x16x32_bf16 v[132:135], v[148:151], v[164:167], v[132:135]
	v_mfma_f32_16x16x32_bf16 v[128:131], v[156:159], v[164:167], v[128:131]
	v_mfma_f32_16x16x32_bf16 v[116:119], v[148:151], v[172:175], v[116:119]
	v_mfma_f32_16x16x32_bf16 v[112:115], v[156:159], v[172:175], v[112:115]
	v_mfma_f32_16x16x32_bf16 v[84:87], v[148:151], v[190:193], v[84:87]
	v_mfma_f32_16x16x32_bf16 v[80:83], v[156:159], v[190:193], v[80:83]
	v_mfma_f32_16x16x32_bf16 v[68:71], v[148:151], v[198:201], v[68:71]
	v_mfma_f32_16x16x32_bf16 v[64:67], v[156:159], v[198:201], v[64:67]
	s_barrier
	s_add_i32 s61, s61, s77
	v_lshl_add_u64 v[202:203], s[34:35], 0, v[232:233]
	s_mov_b32 m0, s61
	ds_read_b128 v[160:163], v221 offset:16384
	ds_read_b128 v[164:167], v221 offset:17408
	ds_read_b128 v[168:171], v221 offset:18432
	ds_read_b128 v[172:175], v221 offset:19456
	ds_read_b128 v[176:179], v221 offset:20480
	ds_read_b128 v[190:193], v221 offset:21504
	ds_read_b128 v[194:197], v221 offset:22528
	ds_read_b128 v[198:201], v221 offset:23552
	global_load_lds_dwordx4 v[202:203], off
	s_add_i32 m0, s61, 0x2000
	s_add_u32 s62, s34, 0x100000
	v_lshl_add_u64 v[204:205], s[34:35], 0, v[184:185]
	s_addc_u32 s63, s35, 0
	s_add_i32 s61, s64, s77
	global_load_lds_dwordx4 v[204:205], off
	v_lshl_add_u64 v[206:207], s[62:63], 0, v[232:233]
	s_mov_b32 m0, s61
	v_lshl_add_u64 v[208:209], s[36:37], 0, v[182:183]
	global_load_lds_dwordx4 v[206:207], off
	v_lshl_add_u64 v[206:207], s[62:63], 0, v[184:185]
	s_add_i32 m0, s61, 0x2000
	s_nop 0
	global_load_lds_dwordx4 v[206:207], off
	v_lshl_add_u64 v[206:207], s[36:37], 0, v[180:181]
	s_waitcnt vmcnt(6)
	s_waitcnt lgkmcnt(0)
	s_barrier
	v_mfma_f32_16x16x32_bf16 v[60:63], v[88:91], v[160:163], 0
	v_mfma_f32_16x16x32_bf16 v[56:59], v[96:99], v[160:163], 0
	v_mfma_f32_16x16x32_bf16 v[44:47], v[88:91], v[168:171], 0
	v_mfma_f32_16x16x32_bf16 v[40:43], v[96:99], v[168:171], 0
	v_mfma_f32_16x16x32_bf16 v[28:31], v[88:91], v[176:179], 0
	v_mfma_f32_16x16x32_bf16 v[24:27], v[96:99], v[176:179], 0
	v_mfma_f32_16x16x32_bf16 v[12:15], v[88:91], v[194:197], 0
	v_mfma_f32_16x16x32_bf16 v[8:11], v[96:99], v[194:197], 0
	v_mfma_f32_16x16x32_bf16 v[60:63], v[92:95], v[164:167], v[60:63]
	v_mfma_f32_16x16x32_bf16 v[56:59], v[100:103], v[164:167], v[56:59]
	v_mfma_f32_16x16x32_bf16 v[44:47], v[92:95], v[172:175], v[44:47]
	v_mfma_f32_16x16x32_bf16 v[40:43], v[100:103], v[172:175], v[40:43]
	v_mfma_f32_16x16x32_bf16 v[28:31], v[92:95], v[190:193], v[28:31]
	v_mfma_f32_16x16x32_bf16 v[24:27], v[100:103], v[190:193], v[24:27]
	v_mfma_f32_16x16x32_bf16 v[12:15], v[92:95], v[198:201], v[12:15]
	v_mfma_f32_16x16x32_bf16 v[8:11], v[100:103], v[198:201], v[8:11]
	v_mfma_f32_16x16x32_bf16 v[52:55], v[144:147], v[160:163], 0
	v_mfma_f32_16x16x32_bf16 v[48:51], v[152:155], v[160:163], 0
	v_mfma_f32_16x16x32_bf16 v[36:39], v[144:147], v[168:171], 0
	v_mfma_f32_16x16x32_bf16 v[32:35], v[152:155], v[168:171], 0
	v_mfma_f32_16x16x32_bf16 v[20:23], v[144:147], v[176:179], 0
	v_mfma_f32_16x16x32_bf16 v[16:19], v[152:155], v[176:179], 0
	v_mfma_f32_16x16x32_bf16 v[4:7], v[144:147], v[194:197], 0
	v_mfma_f32_16x16x32_bf16 v[0:3], v[152:155], v[194:197], 0
	v_mfma_f32_16x16x32_bf16 v[52:55], v[148:151], v[164:167], v[52:55]
	v_mfma_f32_16x16x32_bf16 v[48:51], v[156:159], v[164:167], v[48:51]
	v_mfma_f32_16x16x32_bf16 v[36:39], v[148:151], v[172:175], v[36:39]
	v_mfma_f32_16x16x32_bf16 v[32:35], v[156:159], v[172:175], v[32:35]
	v_mfma_f32_16x16x32_bf16 v[20:23], v[148:151], v[190:193], v[20:23]
	v_mfma_f32_16x16x32_bf16 v[16:19], v[156:159], v[190:193], v[16:19]
	v_mfma_f32_16x16x32_bf16 v[4:7], v[148:151], v[198:201], v[4:7]
	v_mfma_f32_16x16x32_bf16 v[0:3], v[156:159], v[198:201], v[0:3]
	s_barrier
	s_branch .Lzmid_6
	.p2align 6
